# attention steady loop rotated: only the trip test between step B's barrier and the next first score MFMA; rare rescale blocks out of line so the common path takes no branch around them
# speedup vs baseline: 1.0063x; 1.0012x over previous
.Latt_head:
	s_lshl_b32 s14, s14, 1
	v_add_u32_e32 v217, s14, v244
	ds_read_b64_tr_b16 v[208:209], v217 offset:24576
	ds_read_b64_tr_b16 v[210:211], v217 offset:25088
	v_add_f32_e32 v112, v96, v97
	v_add_f32_e32 v112, v98, v112
	v_add_f32_e32 v112, v99, v112
	v_add_f32_e32 v112, v100, v112
	v_add_f32_e32 v112, v101, v112
	v_cvt_pk_bf16_f32 v164, v96, v97
	v_cvt_pk_bf16_f32 v165, v98, v99
	ds_read_b64_tr_b16 v[96:97], v217 offset:28672
	ds_read_b64_tr_b16 v[98:99], v217 offset:29184
	v_add_f32_e32 v112, v102, v112
	v_add_f32_e32 v112, v103, v112
	v_add_f32_e32 v112, v104, v112
	v_add_f32_e32 v144, v105, v112
	v_mfma_f32_32x32x16_bf16 v[112:127], v[200:203], v[172:175], v[64:79]
	v_cvt_pk_bf16_f32 v166, v100, v101
	v_cvt_pk_bf16_f32 v167, v102, v103
	ds_read_b64_tr_b16 v[100:101], v217 offset:25600
	ds_read_b64_tr_b16 v[102:103], v217 offset:26112
	v_mfma_f32_32x32x16_bf16 v[128:143], v[196:199], v[168:171], v[128:143]
	v_add_f32_e32 v144, v106, v144
	v_add_f32_e32 v144, v107, v144
	v_add_f32_e32 v144, v108, v144
	v_add_f32_e32 v144, v109, v144
	v_cvt_pk_bf16_f32 v156, v104, v105
	v_cvt_pk_bf16_f32 v157, v106, v107
	ds_read_b64_tr_b16 v[104:105], v217 offset:29696
	ds_read_b64_tr_b16 v[106:107], v217 offset:30208
	v_mfma_f32_32x32x16_bf16 v[112:127], v[192:195], v[168:171], v[112:127]
	v_add_f32_e32 v144, v110, v144
	v_add_f32_e32 v144, v111, v144
	v_add_f32_e32 v144, v80, v144
	v_add_f32_e32 v144, v81, v144
	v_cvt_pk_bf16_f32 v158, v108, v109
	v_cvt_pk_bf16_f32 v159, v110, v111
	ds_read_b64_tr_b16 v[108:109], v217 offset:26624
	ds_read_b64_tr_b16 v[110:111], v217 offset:27136
	v_mfma_f32_32x32x16_bf16 v[128:143], v[188:191], v[160:163], v[128:143]
	v_add_f32_e32 v144, v82, v144
	v_add_f32_e32 v144, v83, v144
	v_add_f32_e32 v144, v84, v144
	v_add_f32_e32 v144, v85, v144
	v_cvt_pk_bf16_f32 v148, v80, v81
	v_cvt_pk_bf16_f32 v149, v82, v83
	ds_read_b64_tr_b16 v[80:81], v217 offset:30720
	ds_read_b64_tr_b16 v[82:83], v217 offset:31232
	v_mfma_f32_32x32x16_bf16 v[112:127], v[184:187], v[160:163], v[112:127]
	v_add_f32_e32 v144, v86, v144
	v_add_f32_e32 v144, v87, v144
	v_add_f32_e32 v144, v88, v144
	v_add_f32_e32 v144, v89, v144
	v_cvt_pk_bf16_f32 v150, v84, v85
	v_cvt_pk_bf16_f32 v151, v86, v87
	ds_read_b64_tr_b16 v[84:85], v217 offset:27648
	ds_read_b64_tr_b16 v[86:87], v217 offset:28160
	v_mfma_f32_32x32x16_bf16 v[128:143], v[180:183], v[152:155], v[128:143]
	v_add_f32_e32 v144, v90, v144
	v_add_f32_e32 v144, v91, v144
	v_add_f32_e32 v144, v92, v144
	v_add_f32_e32 v180, v93, v144
	v_cvt_pk_bf16_f32 v144, v88, v89
	v_cvt_pk_bf16_f32 v145, v90, v91
	ds_read_b64_tr_b16 v[88:89], v217 offset:31744
	ds_read_b64_tr_b16 v[90:91], v217 offset:32256
	v_mfma_f32_32x32x16_bf16 v[112:127], v[176:179], v[152:155], v[112:127]
	v_add_f32_e32 v146, v94, v180
	v_add_f32_e32 v176, v95, v146
	v_cvt_pk_bf16_f32 v146, v92, v93
	v_cvt_pk_bf16_f32 v147, v94, v95
	s_add_i32 m0, s24, s63
	s_mov_b32 s14, s32
	s_mov_b32 s15, s70
	global_load_lds_dwordx4 v212, s[14:15]
	s_lshl_b32 s14, s22, 1
	s_add_i32 s14, s14, s64
	s_mov_b32 m0, s14
	s_add_i32 s14, s14, 0x1f80
	global_load_lds_dwordx4 v226, s[98:99]
	s_mov_b32 m0, s14
	s_nop 0
	global_load_lds_dwordx4 v226, s[98:99] offset:128
	s_waitcnt lgkmcnt(12)
	v_mfma_f32_32x32x16_bf16 v[32:47], v[164:167], v[208:211], v[32:47]
	v_max_f32_e32 v222, v128, v129
	v_max3_f32 v223, v130, v131, v113
	v_max3_f32 v222, v222, v112, v114
	v_max3_f32 v222, v222, v115, v132
	ds_read_b64_tr_b16 v[92:93], v217 offset:32768
	ds_read_b64_tr_b16 v[94:95], v217 offset:33280
	v_mfma_f32_32x32x16_bf16 v[48:63], v[164:167], v[96:99], v[48:63]
	v_max3_f32 v223, v223, v134, v135
	v_max3_f32 v222, v222, v133, v116
	v_max3_f32 v223, v223, v118, v119
	v_max3_f32 v222, v222, v117, v136
	ds_read_b64_tr_b16 v[96:97], v217 offset:36864
	ds_read_b64_tr_b16 v[98:99], v217 offset:37376
	s_waitcnt lgkmcnt(12)
	v_mfma_f32_32x32x16_bf16 v[32:47], v[156:159], v[100:103], v[32:47]
	v_max3_f32 v223, v223, v138, v139
	v_max3_f32 v222, v222, v137, v120
	v_max3_f32 v223, v223, v122, v123
	v_max3_f32 v222, v222, v121, v140
	ds_read_b64_tr_b16 v[100:101], v217 offset:33792
	ds_read_b64_tr_b16 v[102:103], v217 offset:34304
	v_mfma_f32_32x32x16_bf16 v[48:63], v[156:159], v[104:107], v[48:63]
	v_max3_f32 v223, v223, v142, v143
	v_max3_f32 v222, v222, v141, v124
	v_max3_f32 v223, v223, v126, v127
	v_max3_f32 v222, v222, v125, v223
	ds_read_b64_tr_b16 v[104:105], v217 offset:37888
	ds_read_b64_tr_b16 v[106:107], v217 offset:38400
	s_waitcnt lgkmcnt(12)
	v_mfma_f32_32x32x16_bf16 v[32:47], v[148:151], v[108:111], v[32:47]
	v_mov_b32_e32 v223, v222
	v_add_f32_e32 v215, v249, v176
	s_nop 0
	v_permlane32_swap_b32_e32 v222, v223
	v_max_f32_e32 v222, v222, v223
	v_cmp_lt_f32_e32 vcc, s33, v222
	s_nop 0
	s_mov_b64 s[20:21], vcc
	s_cbranch_vccnz .LBB0_318
.LBB0_311:
	v_exp_f32_e32 v128, v128
	v_exp_f32_e32 v129, v129
	v_exp_f32_e32 v130, v130
	ds_read_b64_tr_b16 v[108:109], v217 offset:34816
	ds_read_b64_tr_b16 v[110:111], v217 offset:35328
	v_mfma_f32_32x32x16_bf16 v[48:63], v[148:151], v[80:83], v[48:63]
	v_exp_f32_e32 v131, v131
	v_exp_f32_e32 v132, v132
	v_exp_f32_e32 v133, v133
	ds_read_b64_tr_b16 v[188:189], v217 offset:38912
	ds_read_b64_tr_b16 v[190:191], v217 offset:39424
	s_waitcnt lgkmcnt(12)
	v_mfma_f32_32x32x16_bf16 v[32:47], v[144:147], v[84:87], v[32:47]
	v_exp_f32_e32 v134, v134
	v_exp_f32_e32 v135, v135
	v_exp_f32_e32 v136, v136
	ds_read_b64_tr_b16 v[84:85], v217 offset:35840
	ds_read_b64_tr_b16 v[86:87], v217 offset:36352
	v_mfma_f32_32x32x16_bf16 v[48:63], v[144:147], v[88:91], v[48:63]
	v_exp_f32_e32 v137, v137
	v_exp_f32_e32 v138, v138
	v_exp_f32_e32 v139, v139
	ds_read_b64_tr_b16 v[88:89], v217 offset:39936
	ds_read_b64_tr_b16 v[90:91], v217 offset:40448
	s_waitcnt lgkmcnt(12)
	v_mfma_f32_32x32x16_bf16 v[16:31], v[164:167], v[92:95], v[16:31]
	v_exp_f32_e32 v140, v140
	v_exp_f32_e32 v141, v141
	v_exp_f32_e32 v142, v142
	v_add_u32_e32 v92, s22, v247
	ds_read_b128 v[80:83], v92
	ds_read_b128 v[200:203], v92 offset:512
	v_mfma_f32_32x32x16_bf16 v[0:15], v[164:167], v[96:99], v[0:15]
	v_exp_f32_e32 v143, v143
	v_exp_f32_e32 v112, v112
	v_exp_f32_e32 v113, v113
	ds_read_b128 v[204:207], v92 offset:2048
	ds_read_b128 v[196:199], v92 offset:2560
	s_waitcnt lgkmcnt(12)
	v_mfma_f32_32x32x16_bf16 v[16:31], v[156:159], v[100:103], v[16:31]
	v_exp_f32_e32 v114, v114
	v_exp_f32_e32 v115, v115
	v_exp_f32_e32 v116, v116
	ds_read_b128 v[192:195], v92 offset:4096
	ds_read_b128 v[184:187], v92 offset:4608
	v_mfma_f32_32x32x16_bf16 v[0:15], v[156:159], v[104:107], v[0:15]
	v_exp_f32_e32 v117, v117
	v_exp_f32_e32 v118, v118
	v_exp_f32_e32 v119, v119
	ds_read_b128 v[180:183], v92 offset:6144
	ds_read_b128 v[176:179], v92 offset:6656
	s_waitcnt lgkmcnt(12)
	v_mfma_f32_32x32x16_bf16 v[16:31], v[148:151], v[108:111], v[16:31]
	v_exp_f32_e32 v120, v120
	v_exp_f32_e32 v121, v121
	v_exp_f32_e32 v122, v122
	v_mfma_f32_32x32x16_bf16 v[0:15], v[148:151], v[188:191], v[0:15]
	v_exp_f32_e32 v123, v123
	v_exp_f32_e32 v124, v124
	v_exp_f32_e32 v125, v125
	s_waitcnt lgkmcnt(8)
	v_mfma_f32_32x32x16_bf16 v[16:31], v[144:147], v[84:87], v[16:31]
	v_exp_f32_e32 v126, v126
	v_exp_f32_e32 v127, v127
	v_mfma_f32_32x32x16_bf16 v[0:15], v[144:147], v[88:91], v[0:15]
	s_waitcnt vmcnt(3) lgkmcnt(0)
	s_barrier
	s_cmp_eq_u64 s[20:21], 0
	s_cbranch_scc0 .Lresc_a

.LBB0_314:
	v_exp_f32_e32 v96, v96
	v_exp_f32_e32 v97, v97
	v_exp_f32_e32 v98, v98
	ds_read_b64_tr_b16 v[140:141], v209 offset:34816
	ds_read_b64_tr_b16 v[142:143], v209 offset:35328
	v_mfma_f32_32x32x16_bf16 v[48:63], v[148:151], v[112:115], v[48:63]
	v_exp_f32_e32 v99, v99
	v_exp_f32_e32 v100, v100
	v_exp_f32_e32 v101, v101
	ds_read_b64_tr_b16 v[112:113], v209 offset:38912
	ds_read_b64_tr_b16 v[114:115], v209 offset:39424
	s_waitcnt lgkmcnt(12)
	v_mfma_f32_32x32x16_bf16 v[32:47], v[144:147], v[116:119], v[32:47]
	v_exp_f32_e32 v102, v102
	v_exp_f32_e32 v103, v103
	v_exp_f32_e32 v104, v104
	ds_read_b64_tr_b16 v[116:117], v209 offset:35840
	ds_read_b64_tr_b16 v[118:119], v209 offset:36352
	v_mfma_f32_32x32x16_bf16 v[48:63], v[144:147], v[120:123], v[48:63]
	v_exp_f32_e32 v105, v105
	v_exp_f32_e32 v106, v106
	v_exp_f32_e32 v107, v107
	ds_read_b64_tr_b16 v[120:121], v209 offset:39936
	ds_read_b64_tr_b16 v[122:123], v209 offset:40448
	s_waitcnt lgkmcnt(12)
	v_mfma_f32_32x32x16_bf16 v[16:31], v[164:167], v[124:127], v[16:31]
	v_exp_f32_e32 v108, v108
	v_exp_f32_e32 v109, v109
	v_exp_f32_e32 v110, v110
	v_add_u32_e32 v124, s66, v247
	ds_read_b128 v[204:207], v124
	ds_read_b128 v[200:203], v124 offset:512
	v_mfma_f32_32x32x16_bf16 v[0:15], v[164:167], v[128:131], v[0:15]
	v_exp_f32_e32 v111, v111
	v_exp_f32_e32 v80, v80
	v_exp_f32_e32 v81, v81
	ds_read_b128 v[196:199], v124 offset:2048
	ds_read_b128 v[192:195], v124 offset:2560
	s_waitcnt lgkmcnt(12)
	v_mfma_f32_32x32x16_bf16 v[16:31], v[156:159], v[132:135], v[16:31]
	v_exp_f32_e32 v82, v82
	v_exp_f32_e32 v83, v83
	v_exp_f32_e32 v84, v84
	ds_read_b128 v[188:191], v124 offset:4096
	ds_read_b128 v[184:187], v124 offset:4608
	v_mfma_f32_32x32x16_bf16 v[0:15], v[156:159], v[136:139], v[0:15]
	v_exp_f32_e32 v85, v85
	v_exp_f32_e32 v86, v86
	v_exp_f32_e32 v87, v87
	ds_read_b128 v[180:183], v124 offset:6144
	ds_read_b128 v[176:179], v124 offset:6656
	s_waitcnt lgkmcnt(12)
	v_mfma_f32_32x32x16_bf16 v[16:31], v[148:151], v[140:143], v[16:31]
	v_exp_f32_e32 v88, v88
	v_exp_f32_e32 v89, v89
	v_exp_f32_e32 v90, v90
	v_mfma_f32_32x32x16_bf16 v[0:15], v[148:151], v[112:115], v[0:15]
	v_exp_f32_e32 v91, v91
	v_exp_f32_e32 v92, v92
	v_exp_f32_e32 v93, v93
	s_waitcnt lgkmcnt(8)
	v_mfma_f32_32x32x16_bf16 v[16:31], v[144:147], v[116:119], v[16:31]
	v_exp_f32_e32 v94, v94
	v_exp_f32_e32 v95, v95
	v_mfma_f32_32x32x16_bf16 v[0:15], v[144:147], v[120:123], v[0:15]
	s_waitcnt vmcnt(3) lgkmcnt(0)
	s_barrier
	s_cmp_eq_u64 s[20:21], 0
	s_cbranch_scc0 .Lresc_b
.LBB0_316:
	s_add_i32 s38, s38, 2
	s_cmp_ge_i32 s38, s23
	s_cbranch_scc1 .Latt_exit
	v_mfma_f32_32x32x16_bf16 v[128:143], v[204:207], v[172:175], v[64:79]
	s_add_u32 s32, s32, s42
	s_addc_u32 s70, s70, s43
	s_add_u32 s98, s98, s42
	s_addc_u32 s99, s99, s43
	s_add_i32 s14, s66, 0x2000
	s_cmpk_lg_i32 s66, 0x4000
	s_cselect_b32 s67, s14, 0
	v_lshl_add_u64 v[218:219], v[218:219], 0, s[42:43]
	v_lshl_add_u64 v[220:221], v[220:221], 0, s[42:43]
	s_mov_b32 s14, s22
	s_mov_b32 s24, s66
	s_mov_b32 s22, s67
	s_branch .Latt_head
.Latt_exit:
	s_add_i32 s14, s66, 0x2000
	s_cmpk_lg_i32 s66, 0x4000
	s_cselect_b32 s67, s14, 0
	v_lshl_add_u64 v[218:219], v[218:219], 0, s[42:43]
	v_lshl_add_u64 v[220:221], v[220:221], 0, s[42:43]
	s_branch .LBB0_325
.Lresc_a:
	s_waitcnt lgkmcnt(0)
	v_add_u32_e32 v208, s65, v248
	ds_read_b128 v[84:87], v208 offset:96
	ds_read_b128 v[88:91], v208 offset:64
	ds_read_b128 v[92:95], v208 offset:32
	ds_read_b128 v[96:99], v208
	s_waitcnt lgkmcnt(3)
	v_pk_mul_f32 v[44:45], v[44:45], v[84:85]
	s_waitcnt lgkmcnt(2)
	v_pk_mul_f32 v[40:41], v[40:41], v[88:89]
	s_waitcnt lgkmcnt(1)
	v_pk_mul_f32 v[36:37], v[36:37], v[92:93]
	v_pk_mul_f32 v[46:47], v[46:47], v[86:87]
	v_pk_mul_f32 v[42:43], v[42:43], v[90:91]
	v_pk_mul_f32 v[38:39], v[38:39], v[94:95]
	s_waitcnt lgkmcnt(0)
	v_pk_mul_f32 v[34:35], v[34:35], v[98:99]
	v_pk_mul_f32 v[32:33], v[32:33], v[96:97]
	v_pk_mul_f32 v[60:61], v[60:61], v[84:85]
	v_pk_mul_f32 v[56:57], v[56:57], v[88:89]
	v_pk_mul_f32 v[52:53], v[52:53], v[92:93]
	v_pk_mul_f32 v[62:63], v[62:63], v[86:87]
	v_pk_mul_f32 v[58:59], v[58:59], v[90:91]
	v_pk_mul_f32 v[54:55], v[54:55], v[94:95]
	v_pk_mul_f32 v[50:51], v[50:51], v[98:99]
	v_pk_mul_f32 v[48:49], v[48:49], v[96:97]
	v_pk_mul_f32 v[28:29], v[28:29], v[84:85]
	v_pk_mul_f32 v[24:25], v[24:25], v[88:89]
	v_pk_mul_f32 v[20:21], v[20:21], v[92:93]
	v_pk_mul_f32 v[30:31], v[30:31], v[86:87]
	v_pk_mul_f32 v[26:27], v[26:27], v[90:91]
	v_pk_mul_f32 v[22:23], v[22:23], v[94:95]
	v_pk_mul_f32 v[18:19], v[18:19], v[98:99]
	v_pk_mul_f32 v[16:17], v[16:17], v[96:97]
	v_pk_mul_f32 v[12:13], v[12:13], v[84:85]
	v_pk_mul_f32 v[8:9], v[8:9], v[88:89]
	v_pk_mul_f32 v[4:5], v[4:5], v[92:93]
	v_pk_mul_f32 v[14:15], v[14:15], v[86:87]
	v_pk_mul_f32 v[10:11], v[10:11], v[90:91]
	v_pk_mul_f32 v[6:7], v[6:7], v[94:95]
	v_pk_mul_f32 v[2:3], v[2:3], v[98:99]
	v_pk_mul_f32 v[0:1], v[0:1], v[96:97]
	s_branch .LBB0_313
.Lresc_b:
	s_waitcnt lgkmcnt(0)
	v_add_u32_e32 v208, s65, v248
	ds_read_b128 v[112:115], v208 offset:96
	ds_read_b128 v[116:119], v208 offset:64
	ds_read_b128 v[120:123], v208 offset:32
	ds_read_b128 v[124:127], v208
	s_waitcnt lgkmcnt(3)
	v_pk_mul_f32 v[44:45], v[44:45], v[112:113]
	s_waitcnt lgkmcnt(2)
	v_pk_mul_f32 v[40:41], v[40:41], v[116:117]
	s_waitcnt lgkmcnt(1)
	v_pk_mul_f32 v[36:37], v[36:37], v[120:121]
	v_pk_mul_f32 v[46:47], v[46:47], v[114:115]
	v_pk_mul_f32 v[42:43], v[42:43], v[118:119]
	v_pk_mul_f32 v[38:39], v[38:39], v[122:123]
	s_waitcnt lgkmcnt(0)
	v_pk_mul_f32 v[34:35], v[34:35], v[126:127]
	v_pk_mul_f32 v[32:33], v[32:33], v[124:125]
	v_pk_mul_f32 v[60:61], v[60:61], v[112:113]
	v_pk_mul_f32 v[56:57], v[56:57], v[116:117]
	v_pk_mul_f32 v[52:53], v[52:53], v[120:121]
	v_pk_mul_f32 v[62:63], v[62:63], v[114:115]
	v_pk_mul_f32 v[58:59], v[58:59], v[118:119]
	v_pk_mul_f32 v[54:55], v[54:55], v[122:123]
	v_pk_mul_f32 v[50:51], v[50:51], v[126:127]
	v_pk_mul_f32 v[48:49], v[48:49], v[124:125]
	v_pk_mul_f32 v[28:29], v[28:29], v[112:113]
	v_pk_mul_f32 v[24:25], v[24:25], v[116:117]
	v_pk_mul_f32 v[20:21], v[20:21], v[120:121]
	v_pk_mul_f32 v[30:31], v[30:31], v[114:115]
	v_pk_mul_f32 v[26:27], v[26:27], v[118:119]
	v_pk_mul_f32 v[22:23], v[22:23], v[122:123]
	v_pk_mul_f32 v[18:19], v[18:19], v[126:127]
	v_pk_mul_f32 v[16:17], v[16:17], v[124:125]
	v_pk_mul_f32 v[12:13], v[12:13], v[112:113]
	v_pk_mul_f32 v[8:9], v[8:9], v[116:117]
	v_pk_mul_f32 v[4:5], v[4:5], v[120:121]
	v_pk_mul_f32 v[14:15], v[14:15], v[114:115]
	v_pk_mul_f32 v[10:11], v[10:11], v[118:119]
	v_pk_mul_f32 v[6:7], v[6:7], v[122:123]
	v_pk_mul_f32 v[2:3], v[2:3], v[126:127]
	v_pk_mul_f32 v[0:1], v[0:1], v[124:125]
	s_branch .LBB0_316
